# GEMM main loops: per-cluster s_setprio flips removed, one static priority raise for waves 0-3 of every workgroup
# speedup vs baseline: 1.0057x; 1.0057x over previous
_Z14fwd_megakernel3Ctx:
	s_load_dwordx8 s[4:11], s[0:1], 0x80
	s_mov_b32 s54, s2
	s_load_dword s2, s[0:1], 0xa8
	s_load_dwordx2 s[86:87], s[0:1], 0xa0
	v_and_b32_e32 v176, 0x3ff, v0
	v_readfirstlane_b32 s90, v176
	s_nop 3
	s_lshr_b32 s90, s90, 6
	s_cmp_ge_u32 s90, 4
	s_cbranch_scc1 .Lprio_done
	s_setprio 1
